# GQA attention also staged by LDS-DMA into XOR-swizzled unpadded K/V tiles (diff + GQA); loads issued behind K-fragment reads
# baseline (speedup 1.0000x reference)
; template <int KIND> ...
;     ...
;         const int krow_l = tid >> 3, kpart = tid & 7;
;     ...
;         float m_ref = 0.f; int first = 1;
;         f32x16 o[NDT], lacc, mneg;
; #pragma unroll
;         for (int dt = 0; dt < NDT; ++dt)
; #pragma unroll
;             for (int j = 0; j < 16; ++j) o[dt][j] = 0.f;
; #pragma unroll
;         for (int j = 0; j < 16; ++j) { lacc[j] = 0.f; mneg[j] = 0.f; }
;         const bf16x8 ones = {(short)0x3F80, (short)0x3F80, (short)0x3F80, (short)0x3F80, (short)0x3F80, (short)0x3F80, (short)0x3F80, (short)0x3F80};
;         ATT_LOAD(0); ATT_STORE(0); __syncthreads();
;         const int koff = kidx * KT + l32 * KSTR + 16 * hi;
;         const int voff = OFF_V + (4 * hi + ((lane & 15) >> 2)) * VSTR + (16 * ((lane >> 4) & 1) + 4 * (lane & 3)) * 2;
;         const int wb = 4 * hi - cs;
;         const int boff0 = OFF_BIAS + 4 * (cs - qc + 15 + wb);
.LBB0_97:
	s_and_b64 s[2:3], s[6:7], exec
	s_movk_i32 s2, 0x880
	s_cselect_b32 s2, s2, 0x800
	s_cmp_ge_i32 s74, s2
	s_cbranch_scc1 .LBB0_171
	v_ashrrev_i32_e32 v3, 31, v198
	v_lshrrev_b32_e32 v3, 29, v3
	v_add_u32_e32 v3, v198, v3
	s_waitcnt vmcnt(0)
	v_ashrrev_i32_e32 v151, 3, v198
	v_and_b32_e32 v2, 7, v196
	v_ashrrev_i32_e32 v152, 3, v3
	v_and_b32_e32 v3, -8, v3
	v_sub_u32_e32 v3, v198, v3
	v_mul_lo_u32 v4, v151, s90
	v_lshlrev_b32_e32 v192, 4, v2
	s_movk_i32 s4, 0xc0
	v_ashrrev_i32_e32 v1, 5, v196
	v_lshlrev_b32_e32 v0, 3, v2
	v_lshlrev_b32_e32 v138, 3, v3
	v_add3_u32 v153, 0, v4, v192
	v_mul_lo_u32 v2, v152, s4
	v_lshlrev_b32_e32 v3, 4, v3
	v_bfe_u32 v4, v196, 2, 2
	v_lshlrev_b32_e32 v136, 3, v1
	v_add3_u32 v154, 0, v2, v3
	v_lshlrev_b32_e32 v3, 4, v1
	v_lshl_or_b32 v1, v1, 2, v4
	v_and_b32_e32 v4, 16, v196
	v_lshlrev_b32_e32 v5, 2, v196
	v_and_or_b32 v4, v5, 12, v4
	v_and_b32_e32 v150, 31, v196
	v_mul_lo_u32 v1, v1, s4
	v_lshlrev_b32_e32 v4, 1, v4
	v_cmp_lt_i32_e32 vcc, v223, v217
	v_ashrrev_i32_e32 v139, 31, v138
	v_mul_u32_u24_e32 v2, 0x90, v150
	v_add3_u32 v156, 0, v1, v4
	s_mul_i32 s4, s38, 0x1200
	v_cndmask_b32_e32 v1, v216, v223, vcc
	s_lshl_b32 s3, s38, 5
	v_ashrrev_i32_e32 v137, 31, v136
	v_add3_u32 v155, 0, v2, v3
	v_lshl_add_u64 v[140:141], s[58:59], 0, v[192:193]
	v_lshl_add_u64 v[142:143], v[138:139], 1, s[58:59]
	s_add_i32 s14, s4, 0
	v_lshlrev_b32_e32 v157, 2, v1
	v_add_u32_e32 v158, 0x80, v152
	v_add_u32_e32 v159, 0x80, v151
	v_lshlrev_b32_e32 v144, 1, v0
	v_bfe_u32 v8, v198, 4, 3
	v_and_b32_e32 v9, 7, v196
	v_xor_b32_e32 v8, v9, v8
	v_lshlrev_b32_e32 v8, 4, v8
	v_add_u32_e32 v144, 0x800, v8
	v_mov_b32_e32 v10, v144
	v_mov_b32_e32 v11, 0
	v_lshl_add_u64 v[140:141], s[58:59], 0, v[10:11]
	v_and_b32_e32 v8, 7, v198
	v_bfe_u32 v9, v198, 4, 1
	v_lshlrev_b32_e32 v9, 2, v9
	v_xor_b32_e32 v8, v8, v9
	v_lshlrev_b32_e32 v8, 3, v8
	v_add_u32_e32 v138, 0x500, v8
	v_mov_b32_e32 v139, 0
	v_lshl_add_u64 v[142:143], v[138:139], 1, s[58:59]
	v_and_b32_e32 v8, 31, v196
	v_lshlrev_b32_e32 v8, 7, v8
	v_lshrrev_b32_e32 v9, 5, v196
	v_bfe_u32 v10, v196, 1, 1
	v_xor_b32_e32 v9, v9, v10
	v_lshl_or_b32 v8, v9, 4, v8
	v_bfe_u32 v9, v196, 2, 2
	v_lshl_or_b32 v155, v9, 5, v8
	v_lshrrev_b32_e32 v8, 5, v196
	v_bfe_u32 v9, v196, 2, 2
	v_lshl_or_b32 v8, v8, 2, v9
	v_lshlrev_b32_e32 v8, 7, v8
	v_bfe_u32 v9, v196, 3, 1
	v_lshl_or_b32 v8, v9, 6, v8
	v_bfe_u32 v9, v196, 4, 1
	v_lshl_or_b32 v8, v9, 5, v8
	v_and_b32_e32 v9, 3, v196
	v_lshl_or_b32 v156, v9, 3, v8
	s_lshl_b32 s18, s38, 10
	s_mov_b32 s15, s74
	s_branch .LBB0_100

; template <int KIND> ...
;     ...
;         float m_ref = 0.f; int first = 1;
;         f32x16 o[NDT], lacc, mneg;
; #pragma unroll
;         for (int dt = 0; dt < NDT; ++dt)
; #pragma unroll
;             for (int j = 0; j < 16; ++j) o[dt][j] = 0.f;
; #pragma unroll
;         for (int j = 0; j < 16; ++j) { lacc[j] = 0.f; mneg[j] = 0.f; }
;         const bf16x8 ones = {(short)0x3F80, (short)0x3F80, (short)0x3F80, (short)0x3F80, (short)0x3F80, (short)0x3F80, (short)0x3F80, (short)0x3F80};
;         ATT_LOAD(0); ATT_STORE(0); __syncthreads();
;         const int koff = kidx * KT + l32 * KSTR + 16 * hi;
;         const int voff = OFF_V + (4 * hi + ((lane & 15) >> 2)) * VSTR + (16 * ((lane >> 4) & 1) + 4 * (lane & 3)) * 2;
;         const int wb = 4 * hi - cs;
;         const int boff0 = OFF_BIAS + 4 * (cs - qc + 15 + wb);
;         for (int t = 0; t < nt; ++t) {
;             if (t + 1 < nt) ATT_LOAD(t + 1);
;             bool active = true;
;             if (KIND == 0 && t < n1) { const int kr = kr_lo + t; active = (kr >= rs_w) && (kr < rs_w + 8); }
;             if (__builtin_amdgcn_readfirstlane((int)active)) {
;                 const int buf = t & 1;
;                 bf16x8 kf[8];
; #pragma unroll
;                 for (int t4 = 0; t4 < 4; ++t4) { kf[2 * t4] = *(const LAS bf16x8*)(lds + buf * KBUF + koff + 32 * t4); kf[2 * t4 + 1] = *(const LAS bf16x8*)(lds + buf * KBUF + koff + 32 * KSTR + 32 * t4); }
;                 __builtin_amdgcn_sched_barrier(0);
;                 f32x16 s0, s1;
; #pragma unroll
;                 for (int t4 = 0; t4 < 4; ++t4) {
;                     s0 = __builtin_amdgcn_mfma_f32_32x32x16_bf16(kf[2 * t4], qf[t4], t4 == 0 ? mneg : s0, 0, 0, 0);
;                     s1 = __builtin_amdgcn_mfma_f32_32x32x16_bf16(kf[2 * t4 + 1], qf[t4], t4 == 0 ? mneg : s1, 0, 0, 0);
;                 }
;     ...
;                 const float mx0 = fmaxf(s1[15], s0[15]);
;                 float mxa = max3f(mx0, s0[0], s1[0]), mxb = max3f(mx0, s0[1], s1[1]);
; #pragma unroll
;                 for (int j = 2; j < 15; j += 2) { mxa = max3f(mxa, s0[j], s1[j]); mxb = max3f(mxb, s0[j + 1], s1[j + 1]); }
;                 float mx = fmaxf(mxa, mxb);
;                 if (first || __builtin_amdgcn_ballot_w64(mx > 8.0f) != 0ull) {
;                     mx = fmaxf(mx, __shfl_xor(mx, 32));
;                     const float d = first ? mx : fmaxf(mx, 0.f);
.LBB0_108:
	s_add_i32 s16, s19, 0x8000
	s_add_i32 s4, s20, s3
	s_lshl_b32 s12, s17, 6
	s_lshl_b32 s96, s17, 7
	v_add_u32_e32 v2, s4, v150
	v_mov_b64_e32 v[0:1], s[58:59]
	s_and_b64 s[20:21], s[10:11], exec
	v_mad_i64_i32 v[2:3], s[20:21], v2, s23, v[0:1]
	s_cselect_b32 s22, s13, s16
	v_lshl_add_u64 v[8:9], v[2:3], 0, s[96:97]
	v_add_u32_e32 v2, s22, v151
	s_lshl_b32 s17, s17, 5
	v_add_u32_e32 v4, s22, v152
	v_mad_i64_i32 v[2:3], s[20:21], v2, s23, v[0:1]
	s_and_b32 s96, s17, 0xffffff80
	v_mad_i64_i32 v[0:1], s[20:21], v4, s23, v[0:1]
	v_lshl_add_u64 v[2:3], v[2:3], 0, s[96:97]
	v_mov_b32_e32 v145, v193
	v_lshl_add_u64 v[0:1], v[0:1], 0, s[96:97]
	v_lshl_add_u64 v[2:3], v[2:3], 0, v[144:145]
	v_lshl_add_u64 v[4:5], v[138:139], 1, v[0:1]
	s_mov_b32 m0, s18
	s_nop 0
	global_load_lds_dwordx4 v[2:3], off
	s_or_b32 s17, s13, 64
	s_add_i32 m0, s18, 0x4000
	s_nop 0
	global_load_lds_dwordx4 v[4:5], off
	s_add_i32 s19, s19, 0x8040
	s_and_b64 s[10:11], s[10:11], exec
	v_lshl_add_u64 v[8:9], v[136:137], 1, v[8:9]
	s_cselect_b32 s10, s17, s19
	v_lshl_add_u64 v[148:149], v[140:141], 0, s[96:97]
	v_lshl_add_u64 v[146:147], v[142:143], 0, s[96:97]
	global_load_dwordx4 v[116:119], v[8:9], off
	global_load_dwordx4 v[112:115], v[8:9], off offset:32
	global_load_dwordx4 v[108:111], v[8:9], off offset:64
	global_load_dwordx4 v[104:107], v[8:9], off offset:96
	v_add_u32_e32 v8, s10, v151
	v_add_u32_e32 v10, s10, v152
	v_mad_i64_i32 v[8:9], s[10:11], v8, s23, v[148:149]
	v_mad_i64_i32 v[10:11], s[10:11], v10, s23, v[146:147]
	s_waitcnt vmcnt(4)
	s_barrier
	s_add_i32 m0, s18, 0x2000
	v_xor_b32_e32 v174, 32, v155
	global_load_lds_dwordx4 v[8:9], off
	s_add_i32 m0, s18, 0x6000
	v_xor_b32_e32 v175, 64, v155
	global_load_lds_dwordx4 v[10:11], off
	v_xor_b32_e32 v176, 0x60, v155
	v_xor_b32_e32 v177, 64, v156
	ds_read_b128 v[0:3], v155
	ds_read_b128 v[32:35], v174
	ds_read_b128 v[16:19], v155 offset:4096
	ds_read_b128 v[36:39], v174 offset:4096
	ds_read_b128 v[40:43], v175
	ds_read_b128 v[44:47], v176
	ds_read_b128 v[48:51], v175 offset:4096
	ds_read_b128 v[52:55], v176 offset:4096
	s_waitcnt vmcnt(5) lgkmcnt(7)
	v_mfma_f32_32x32x16_bf16 v[0:15], v[0:3], v[116:119], 0
	ds_read_b64_tr_b16 v[72:73], v156 offset:16384
	ds_read_b64_tr_b16 v[74:75], v156 offset:17408
	ds_read_b64_tr_b16 v[78:79], v177 offset:17408
	ds_read_b64_tr_b16 v[76:77], v177 offset:16384
	ds_read_b64_tr_b16 v[80:81], v156 offset:18432
	ds_read_b64_tr_b16 v[82:83], v156 offset:19456
	ds_read_b64_tr_b16 v[86:87], v177 offset:19456
	s_waitcnt lgkmcnt(12)
	v_mfma_f32_32x32x16_bf16 v[16:31], v[16:19], v[116:119], 0
	ds_read_b64_tr_b16 v[84:85], v177 offset:18432
	s_waitcnt vmcnt(4)
	v_mfma_f32_32x32x16_bf16 v[0:15], v[32:35], v[112:115], v[0:15]
	s_waitcnt lgkmcnt(12)
	v_mfma_f32_32x32x16_bf16 v[16:31], v[36:39], v[112:115], v[16:31]
	s_waitcnt vmcnt(3) lgkmcnt(11)
	v_mfma_f32_32x32x16_bf16 v[0:15], v[40:43], v[108:111], v[0:15]
	s_waitcnt lgkmcnt(9)
	v_mfma_f32_32x32x16_bf16 v[16:31], v[48:51], v[108:111], v[16:31]
	s_waitcnt vmcnt(2)
	v_mfma_f32_32x32x16_bf16 v[0:15], v[44:47], v[104:107], v[0:15]
	s_waitcnt lgkmcnt(8)
	v_mfma_f32_32x32x16_bf16 v[16:31], v[52:55], v[104:107], v[16:31]
	s_nop 9
	v_max_f32_e32 v32, v15, v15
	s_nop 0
	v_max_f32_e32 v33, v31, v31
	v_max_f32_e32 v32, v33, v32
	v_max3_f32 v33, v32, v0, v16
	v_max3_f32 v32, v32, v1, v17
	s_nop 0
	v_max3_f32 v33, v33, v2, v18
	v_max3_f32 v32, v32, v3, v19
	s_nop 0
	v_max3_f32 v33, v33, v4, v20
	v_max3_f32 v32, v32, v5, v21
	s_nop 0
	v_max3_f32 v33, v33, v6, v22
	v_max3_f32 v32, v32, v7, v23
	s_nop 0
	v_max3_f32 v33, v33, v8, v24
	v_max3_f32 v32, v32, v9, v25
	s_nop 0
	v_max3_f32 v33, v33, v10, v26
	v_max3_f32 v32, v32, v11, v27
	s_nop 0
	v_max3_f32 v33, v33, v12, v28
	v_max3_f32 v32, v32, v13, v29
	s_nop 0
	v_max3_f32 v33, v33, v14, v30
	v_max3_f32 v32, v32, v15, v31
	s_nop 0
	v_max_f32_e32 v32, v32, v32
	v_max_f32_e32 v33, v33, v33
	v_max_f32_e32 v32, v33, v32
	ds_bpermute_b32 v33, v157, v32
	s_waitcnt lgkmcnt(0)
	v_max_f32_e32 v33, v33, v33
	v_max_f32_e32 v48, v32, v33
	v_sub_f32_e32 v0, v0, v48
	v_sub_f32_e32 v1, v1, v48
	v_sub_f32_e32 v2, v2, v48
	v_sub_f32_e32 v3, v3, v48
	v_sub_f32_e32 v4, v4, v48
	v_sub_f32_e32 v5, v5, v48
	v_sub_f32_e32 v6, v6, v48
	v_sub_f32_e32 v7, v7, v48
	v_sub_f32_e32 v8, v8, v48
	v_sub_f32_e32 v9, v9, v48
	v_sub_f32_e32 v10, v10, v48
	v_sub_f32_e32 v11, v11, v48
	v_sub_f32_e32 v12, v12, v48
	v_sub_f32_e32 v13, v13, v48
	v_sub_f32_e32 v14, v14, v48
	v_sub_f32_e32 v15, v15, v48
	v_exp_f32_e32 v0, v0
	v_exp_f32_e32 v1, v1
	v_exp_f32_e32 v2, v2
	v_exp_f32_e32 v3, v3
	v_exp_f32_e32 v4, v4
	v_exp_f32_e32 v5, v5
	v_exp_f32_e32 v6, v6
	v_exp_f32_e32 v7, v7
	v_exp_f32_e32 v8, v8
	v_exp_f32_e32 v9, v9
	v_exp_f32_e32 v10, v10
	v_exp_f32_e32 v11, v11
	v_exp_f32_e32 v12, v12
	v_exp_f32_e32 v13, v13
	v_exp_f32_e32 v14, v14
	v_exp_f32_e32 v15, v15
	v_sub_f32_e32 v32, 0, v48
	v_sub_f32_e32 v16, v16, v48
	v_sub_f32_e32 v17, v17, v48
	v_sub_f32_e32 v18, v18, v48
	v_sub_f32_e32 v19, v19, v48
	v_mov_b32_e32 v33, v32
	v_mov_b32_e32 v34, v32
	v_mov_b32_e32 v35, v32
	v_mov_b32_e32 v36, v32
	v_mov_b32_e32 v37, v32
	v_mov_b32_e32 v38, v32
	v_mov_b32_e32 v39, v32
	v_mov_b32_e32 v40, v32
	v_mov_b32_e32 v41, v32
	v_mov_b32_e32 v42, v32
	v_mov_b32_e32 v43, v32
	v_mov_b32_e32 v44, v32
	v_mov_b32_e32 v45, v32
	v_mov_b32_e32 v46, v32
	v_mov_b32_e32 v47, v32
	v_cvt_pk_bf16_f32 v0, v0, v1
	v_cvt_pk_bf16_f32 v1, v2, v3
	v_cvt_pk_bf16_f32 v2, v4, v5
	v_cvt_pk_bf16_f32 v3, v6, v7
	v_sub_f32_e32 v96, v20, v48
	v_sub_f32_e32 v97, v21, v48
	v_sub_f32_e32 v98, v22, v48
	v_sub_f32_e32 v99, v23, v48
	v_sub_f32_e32 v100, v24, v48
	v_sub_f32_e32 v101, v25, v48
; template <int KIND> ...
;     ...
; #pragma unroll
;                 for (int j = 0; j < 16; ++j) s0[j] = __builtin_amdgcn_exp2f(s0[j]);
;                 bf16x8 pf[4];
; #pragma unroll
;                 for (int s = 0; s < 2; ++s) { u32x4 w; w.x = pk2n(s0[8 * s + 0], s0[8 * s + 1]); w.y = pk2n(s0[8 * s + 2], s0[8 * s + 3]); w.z = pk2n(s0[8 * s + 4], s0[8 * s + 5]); w.w = pk2n(s0[8 * s + 6], s0[8 * s + 7]);
;                     pf[s] = __builtin_bit_cast(bf16x8, w); }
;                 __builtin_amdgcn_sched_barrier(0);
; #pragma unroll
;                 for (int s = 0; s < 2; ++s)
; #pragma unroll
;                     for (int dt = 0; dt < NDT; ++dt) {
;                         vfb[s][dt][0] = __builtin_amdgcn_ds_read_tr16_b64_v4i16((LAS s16x4*)(lds + buf * VBUF + voff + (16 * (s + 2)) * VSTR + 64 * dt));
;                         vfb[s][dt][1] = __builtin_amdgcn_ds_read_tr16_b64_v4i16((LAS s16x4*)(lds + buf * VBUF + voff + (16 * (s + 2) + 8) * VSTR + 64 * dt)); }
;                 {
;                     constexpr int NM = 2 * (1 + NDT);
;                     int mi = 0;
; #pragma unroll
;                     for (int s = 0; s < 2; ++s) {
;                         lacc = __builtin_amdgcn_mfma_f32_32x32x16_bf16(ones, pf[s], lacc, 0, 0, 0);
; #pragma unroll
;                         for (int j = (mi * 16) / NM; j < ((mi + 1) * 16) / NM; ++j) s1[j] = __builtin_amdgcn_exp2f(s1[j]);
;                         ++mi;
; #pragma unroll
;                         for (int dt = 0; dt < NDT; ++dt) {
;                             const s16x4 va = vfa[s][dt][0], vb = vfa[s][dt][1];
;                             const bf16x8 vf = {va[0], va[1], va[2], va[3], vb[0], vb[1], vb[2], vb[3]};
;                             o[dt] = __builtin_amdgcn_mfma_f32_32x32x16_bf16(vf, pf[s], o[dt], 0, 0, 0);
; #pragma unroll
;                             for (int j = (mi * 16) / NM; j < ((mi + 1) * 16) / NM; ++j) s1[j] = __builtin_amdgcn_exp2f(s1[j]);
;                             ++mi;
;                         }
;                     }
; #pragma unroll
;                     for (int q = 0; q < 2; ++q) { u32x4 w; w.x = pk2n(s1[8 * q + 0], s1[8 * q + 1]); w.y = pk2n(s1[8 * q + 2], s1[8 * q + 3]); w.z = pk2n(s1[8 * q + 4], s1[8 * q + 5]); w.w = pk2n(s1[8 * q + 6], s1[8 * q + 7]);
;                         pf[q + 2] = __builtin_bit_cast(bf16x8, w); }
; #pragma unroll
	v_sub_f32_e32 v102, v26, v48
	v_sub_f32_e32 v103, v27, v48
	v_sub_f32_e32 v120, v28, v48
	v_sub_f32_e32 v121, v29, v48
	v_sub_f32_e32 v122, v30, v48
	v_sub_f32_e32 v123, v31, v48
	v_cvt_pk_bf16_f32 v88, v8, v9
	v_cvt_pk_bf16_f32 v89, v10, v11
	v_cvt_pk_bf16_f32 v90, v12, v13
	v_cvt_pk_bf16_f32 v91, v14, v15
	v_mov_b64_e32 v[94:95], s[86:87]
	v_mov_b64_e32 v[92:93], s[84:85]
	v_exp_f32_e32 v124, v16
	v_exp_f32_e32 v125, v17
	v_mfma_f32_32x32x16_bf16 v[48:63], v[92:95], v[0:3], 0
	v_exp_f32_e32 v126, v18
	v_exp_f32_e32 v127, v19
	v_mfma_f32_32x32x16_bf16 v[16:31], v[72:75], v[0:3], 0
	ds_read_b64_tr_b16 v[72:73], v156 offset:20480
	ds_read_b64_tr_b16 v[74:75], v156 offset:21504
	v_mfma_f32_32x32x16_bf16 v[0:15], v[76:79], v[0:3], 0
	ds_read_b64_tr_b16 v[76:77], v177 offset:20480
	ds_read_b64_tr_b16 v[78:79], v177 offset:21504
	v_mfma_f32_32x32x16_bf16 v[0:15], v[84:87], v[88:91], v[0:15]
	v_exp_f32_e32 v128, v96
	v_exp_f32_e32 v129, v97
	v_exp_f32_e32 v130, v98
	v_exp_f32_e32 v131, v99
	v_exp_f32_e32 v132, v100
	v_exp_f32_e32 v133, v101
	v_exp_f32_e32 v134, v102
	v_exp_f32_e32 v135, v103
	v_exp_f32_e32 v120, v120
	v_exp_f32_e32 v123, v123
	v_mfma_f32_32x32x16_bf16 v[48:63], v[92:95], v[88:91], v[48:63]
	v_exp_f32_e32 v121, v121
	v_exp_f32_e32 v122, v122
	v_cvt_pk_bf16_f32 v100, v124, v125
	v_cvt_pk_bf16_f32 v101, v126, v127
	ds_read_b64_tr_b16 v[96:97], v156 offset:22528
	ds_read_b64_tr_b16 v[98:99], v156 offset:23552
	v_cvt_pk_bf16_f32 v86, v120, v121
	v_mfma_f32_32x32x16_bf16 v[16:31], v[80:83], v[88:91], v[16:31]
	ds_read_b64_tr_b16 v[80:81], v177 offset:22528
	ds_read_b64_tr_b16 v[82:83], v177 offset:23552
	v_cvt_pk_bf16_f32 v102, v128, v129
	v_cvt_pk_bf16_f32 v103, v130, v131
	v_cvt_pk_bf16_f32 v84, v132, v133
	v_cvt_pk_bf16_f32 v85, v134, v135
	v_cvt_pk_bf16_f32 v87, v122, v123
	s_waitcnt lgkmcnt(6)
	v_mfma_f32_32x32x16_bf16 v[16:31], v[72:75], v[100:103], v[16:31]
	s_waitcnt lgkmcnt(4)
	v_mfma_f32_32x32x16_bf16 v[0:15], v[76:79], v[100:103], v[0:15]
	v_mfma_f32_32x32x16_bf16 v[48:63], v[92:95], v[100:103], v[48:63]
	s_waitcnt lgkmcnt(2)
	v_mfma_f32_32x32x16_bf16 v[16:31], v[96:99], v[84:87], v[16:31]
	s_waitcnt lgkmcnt(0)
	v_mfma_f32_32x32x16_bf16 v[0:15], v[80:83], v[84:87], v[0:15]
	v_mfma_f32_32x32x16_bf16 v[48:63], v[92:95], v[84:87], v[48:63]
	s_mov_b32 s10, -2
	v_mov_b32_e32 v145, v159
	v_mov_b32_e32 v160, v158
	v_readlane_b32 s82, v254, 54
	s_movk_i32 s83, 0x1000
	v_readlane_b32 s91, v255, 7
	s_waitcnt vmcnt(0)
	s_waitcnt lgkmcnt(0)
	s_barrier
	s_branch .LBB0_110
.LBB0_109:
	s_nop 0
	v_exp_f32_e32 v80, v80
	v_exp_f32_e32 v81, v81
	v_exp_f32_e32 v82, v82
	v_exp_f32_e32 v83, v83
	v_exp_f32_e32 v84, v84
	v_exp_f32_e32 v85, v85
	v_exp_f32_e32 v86, v86
	v_exp_f32_e32 v87, v87
	v_exp_f32_e32 v88, v88
	v_exp_f32_e32 v89, v89
	v_exp_f32_e32 v90, v90
	v_exp_f32_e32 v91, v91
	v_exp_f32_e32 v92, v92
	v_exp_f32_e32 v93, v93
	v_exp_f32_e32 v94, v94
	v_exp_f32_e32 v95, v95
	v_cvt_pk_bf16_f32 v80, v80, v81
	v_cvt_pk_bf16_f32 v81, v82, v83
	v_cvt_pk_bf16_f32 v82, v84, v85
	v_cvt_pk_bf16_f32 v83, v86, v87
	v_cvt_pk_bf16_f32 v84, v88, v89
	v_cvt_pk_bf16_f32 v85, v90, v91
	v_cvt_pk_bf16_f32 v86, v92, v93
	v_cvt_pk_bf16_f32 v87, v94, v95
	s_waitcnt lgkmcnt(6)
	v_mfma_f32_32x32x16_bf16 v[16:31], v[132:135], v[80:83], v[16:31]
	v_mov_b64_e32 v[90:91], s[86:87]
	v_mov_b64_e32 v[88:89], s[84:85]
	v_exp_f32_e32 v92, v64
	v_exp_f32_e32 v93, v65
	ds_read_b64_tr_b16 v[64:65], v161 offset:20480
	v_mfma_f32_32x32x16_bf16 v[48:63], v[88:91], v[80:83], v[48:63]
	v_exp_f32_e32 v94, v66
	v_exp_f32_e32 v95, v67
	v_exp_f32_e32 v132, v68
	v_exp_f32_e32 v133, v69
	ds_read_b64_tr_b16 v[66:67], v161 offset:21504
	ds_read_b64_tr_b16 v[68:69], v177 offset:20480
	s_waitcnt lgkmcnt(7)
	v_mfma_f32_32x32x16_bf16 v[0:15], v[128:131], v[80:83], v[0:15]
	v_exp_f32_e32 v134, v70
	v_exp_f32_e32 v135, v71
	v_exp_f32_e32 v128, v72
	v_exp_f32_e32 v129, v73
	ds_read_b64_tr_b16 v[70:71], v177 offset:21504
	ds_read_b64_tr_b16 v[72:73], v161 offset:22528
	v_mfma_f32_32x32x16_bf16 v[48:63], v[88:91], v[84:87], v[48:63]
	v_exp_f32_e32 v130, v74
	v_exp_f32_e32 v131, v75
	v_exp_f32_e32 v162, v76
	v_exp_f32_e32 v163, v77
	ds_read_b64_tr_b16 v[74:75], v161 offset:23552
	ds_read_b64_tr_b16 v[76:77], v177 offset:22528
	s_waitcnt lgkmcnt(9)
	v_mfma_f32_32x32x16_bf16 v[16:31], v[124:127], v[84:87], v[16:31]
	v_exp_f32_e32 v164, v78
	v_exp_f32_e32 v165, v79
	v_cvt_pk_bf16_f32 v80, v92, v93
	v_cvt_pk_bf16_f32 v81, v94, v95
	ds_read_b64_tr_b16 v[78:79], v177 offset:23552
	s_waitcnt lgkmcnt(8)
	v_mfma_f32_32x32x16_bf16 v[0:15], v[120:123], v[84:87], v[0:15]
	v_cvt_pk_bf16_f32 v82, v132, v133
	v_cvt_pk_bf16_f32 v83, v134, v135
	v_cvt_pk_bf16_f32 v84, v128, v129
	v_cvt_pk_bf16_f32 v85, v130, v131
	v_cvt_pk_bf16_f32 v86, v162, v163
	v_cvt_pk_bf16_f32 v87, v164, v165
	s_waitcnt lgkmcnt(6)
	v_mfma_f32_32x32x16_bf16 v[16:31], v[64:67], v[80:83], v[16:31]
	s_waitcnt lgkmcnt(4)
	v_mfma_f32_32x32x16_bf16 v[0:15], v[68:71], v[80:83], v[0:15]
	v_mfma_f32_32x32x16_bf16 v[48:63], v[88:91], v[80:83], v[48:63]
	s_waitcnt lgkmcnt(2)
	v_mfma_f32_32x32x16_bf16 v[16:31], v[72:75], v[84:87], v[16:31]
	s_waitcnt lgkmcnt(0)
	v_mfma_f32_32x32x16_bf16 v[0:15], v[76:79], v[84:87], v[0:15]
	v_mfma_f32_32x32x16_bf16 v[48:63], v[88:91], v[84:87], v[48:63]
	s_and_b32 s17, s11, 1
	s_lshl_b32 s19, s17, 13
	s_lshl_b32 s17, s17, 13
	s_add_i32 s10, s10, 1
	v_add_u32_e32 v160, 64, v160
	s_cmp_eq_u32 s5, s10
	v_add_u32_e32 v145, 64, v145
	s_waitcnt vmcnt(0) lgkmcnt(0)
	s_barrier
	s_cbranch_scc1 .LBB0_112
; #define LAS __attribute__((address_space(3)))
; template <int KIND> ...
;     ...
;             if (t + 1 < nt) ATT_LOAD(t + 1);
;             bool active = true;
;             if (KIND == 0 && t < n1) { const int kr = kr_lo + t; active = (kr >= rs_w) && (kr < rs_w + 8); }
;             if (__builtin_amdgcn_readfirstlane((int)active)) {
;                 const int buf = t & 1;
;                 bf16x8 kf[8];
; #pragma unroll
;                 for (int t4 = 0; t4 < 4; ++t4) { kf[2 * t4] = *(const LAS bf16x8*)(lds + buf * KBUF + koff + 32 * t4); kf[2 * t4 + 1] = *(const LAS bf16x8*)(lds + buf * KBUF + koff + 32 * KSTR + 32 * t4); }
;                 __builtin_amdgcn_sched_barrier(0);
;                 f32x16 s0, s1;
; #pragma unroll
;                 for (int t4 = 0; t4 < 4; ++t4) {
;                     s0 = __builtin_amdgcn_mfma_f32_32x32x16_bf16(kf[2 * t4], qf[t4], t4 == 0 ? mneg : s0, 0, 0, 0);
;                     s1 = __builtin_amdgcn_mfma_f32_32x32x16_bf16(kf[2 * t4 + 1], qf[t4], t4 == 0 ? mneg : s1, 0, 0, 0);
;                 }
;                 float ab0[16], ab1[16];
;                 const bool na_lat = (KIND == 0) && (t < n1);
;                 if (na_lat) {
;                     const int bo = boff0 + (kr_lo + t - qr + 7) * 124;
; #pragma unroll
;                     for (int j = 0; j < 16; ++j) {
;                         const int C0 = 8 * (j >> 2) + (j & 3), C1 = 32 + C0;
;                         const float b0 = *(const LAS float*)(lds + bo + 4 * C0), b1 = *(const LAS float*)(lds + bo + 4 * C1);
;                         ab0[j] = ((unsigned)(wb + C0) < 16u) ? b0 : -1e30f;
;                         ab1[j] = ((unsigned)(wb + C1) < 16u) ? b1 : -1e30f;
;                     }
; #pragma unroll
;                     for (int i = 0; i < 8; ++i) { __builtin_amdgcn_sched_group_barrier(0x008, 1, 0); __builtin_amdgcn_sched_group_barrier(0x100, 4, 0); __builtin_amdgcn_sched_group_barrier(0x002, 12, 0); }
;                 }
;                 __builtin_amdgcn_sched_barrier(0);
;                 s16x4 vfa[2][NDT][2], vfb[2][NDT][2];
; #pragma unroll
;                 for (int s = 0; s < 2; ++s)
; #pragma unroll
;                     for (int dt = 0; dt < NDT; ++dt) {
;                         vfa[s][dt][0] = __builtin_amdgcn_ds_read_tr16_b64_v4i16((LAS s16x4*)(lds + buf * VBUF + voff + (16 * s) * VSTR + 64 * dt));
.LBB0_110:
	s_add_i32 s17, s10, -1
	s_add_i32 s11, s10, 4
	s_and_b32 s17, s17, 1
	s_lshl_b32 s19, s17, 13
	v_add_u32_e32 v68, s19, v155
	v_xor_b32_e32 v174, 32, v68
	v_xor_b32_e32 v175, 64, v68
	v_xor_b32_e32 v176, 0x60, v68
	ds_read_b128 v[64:67], v68
	ds_read_b128 v[120:123], v174
	ds_read_b128 v[124:127], v68 offset:4096
	ds_read_b128 v[128:131], v174 offset:4096
	ds_read_b128 v[132:135], v175
	ds_read_b128 v[162:165], v176
	ds_read_b128 v[166:169], v175 offset:4096
	ds_read_b128 v[170:173], v176 offset:4096
	s_cmp_lt_u32 s11, s5
	s_cselect_b32 s20, 0, s5
	s_cselect_b32 s21, s13, s16
	s_lshl_b32 s20, s20, 6
	s_sub_i32 s20, s21, s20
	s_and_b32 s21, s11, 1
	s_lshl_b32 s21, s21, 13
	s_add_i32 s21, s21, s18
	v_add_u32_e32 v182, s20, v145
	v_mad_i64_i32 v[182:183], vcc, v182, s23, v[148:149]
	s_mov_b32 m0, s21
	v_add_u32_e32 v184, s20, v160
	global_load_lds_dwordx4 v[182:183], off
	v_mad_i64_i32 v[184:185], vcc, v184, s23, v[146:147]
	s_add_i32 m0, s21, 0x4000
	s_nop 0
	global_load_lds_dwordx4 v[184:185], off
	s_waitcnt lgkmcnt(7)
	v_mfma_f32_32x32x16_bf16 v[80:95], v[64:67], v[116:119], v[32:47]
	s_lshl_b32 s17, s17, 13
	v_add_u32_e32 v161, s17, v156
	v_xor_b32_e32 v177, 64, v161
	s_waitcnt lgkmcnt(5)
	v_mfma_f32_32x32x16_bf16 v[64:79], v[124:127], v[116:119], v[32:47]
	v_mfma_f32_32x32x16_bf16 v[80:95], v[120:123], v[112:115], v[80:95]
	s_waitcnt lgkmcnt(4)
	v_mfma_f32_32x32x16_bf16 v[64:79], v[128:131], v[112:115], v[64:79]
	s_waitcnt lgkmcnt(3)
	v_mfma_f32_32x32x16_bf16 v[80:95], v[132:135], v[108:111], v[80:95]
	ds_read_b64_tr_b16 v[132:133], v161 offset:16384
	ds_read_b64_tr_b16 v[134:135], v161 offset:17408
	ds_read_b64_tr_b16 v[130:131], v177 offset:17408
	ds_read_b64_tr_b16 v[128:129], v177 offset:16384
	ds_read_b64_tr_b16 v[124:125], v161 offset:18432
	ds_read_b64_tr_b16 v[126:127], v161 offset:19456
	ds_read_b64_tr_b16 v[122:123], v177 offset:19456
	ds_read_b64_tr_b16 v[120:121], v177 offset:18432
	s_waitcnt lgkmcnt(9)
	v_mfma_f32_32x32x16_bf16 v[64:79], v[166:169], v[108:111], v[64:79]
	v_mfma_f32_32x32x16_bf16 v[80:95], v[162:165], v[104:107], v[80:95]
	s_waitcnt lgkmcnt(8)
	v_mfma_f32_32x32x16_bf16 v[64:79], v[170:173], v[104:107], v[64:79]
	s_nop 9
	v_max_f32_e32 v162, v95, v95
	s_nop 0
	v_max_f32_e32 v163, v79, v79
	v_max_f32_e32 v162, v163, v162
	v_max3_f32 v163, v162, v80, v64
	v_max3_f32 v162, v162, v81, v65
	s_mov_b32 s17, 0x41000000
	v_max3_f32 v163, v163, v82, v66
	v_max3_f32 v162, v162, v83, v67
	s_nop 0
	v_max3_f32 v163, v163, v84, v68
	v_max3_f32 v162, v162, v85, v69
	s_nop 0
	v_max3_f32 v163, v163, v86, v70
	v_max3_f32 v162, v162, v87, v71
	s_nop 0
	v_max3_f32 v163, v163, v88, v72
	v_max3_f32 v162, v162, v89, v73
	s_nop 0
	v_max3_f32 v163, v163, v90, v74
	v_max3_f32 v162, v162, v91, v75
	s_nop 0
	v_max3_f32 v163, v163, v92, v76
	v_max3_f32 v162, v162, v93, v77
	s_nop 0
	v_max3_f32 v163, v163, v94, v78
	v_max3_f32 v162, v162, v95, v79
	s_nop 0
	v_max_f32_e32 v162, v162, v162
	v_max_f32_e32 v163, v163, v163
	v_max_f32_e32 v162, v163, v162
	v_cmp_lt_f32_e32 vcc, s17, v162
	s_cbranch_vccz .LBB0_109
	ds_bpermute_b32 v163, v157, v162
	s_waitcnt lgkmcnt(0)
	v_max3_f32 v162, v162, v163, 0
	v_exp_f32_e64 v164, -v162
	v_pk_add_f32 v[80:81], v[80:81], v[162:163] op_sel_hi:[1,0] neg_lo:[0,1] neg_hi:[0,1]
	v_pk_add_f32 v[64:65], v[64:65], v[162:163] op_sel_hi:[1,0] neg_lo:[0,1] neg_hi:[0,1]
	v_pk_add_f32 v[82:83], v[82:83], v[162:163] op_sel_hi:[1,0] neg_lo:[0,1] neg_hi:[0,1]
	v_pk_add_f32 v[66:67], v[66:67], v[162:163] op_sel_hi:[1,0] neg_lo:[0,1] neg_hi:[0,1]
	v_pk_add_f32 v[84:85], v[84:85], v[162:163] op_sel_hi:[1,0] neg_lo:[0,1] neg_hi:[0,1]
	v_pk_add_f32 v[68:69], v[68:69], v[162:163] op_sel_hi:[1,0] neg_lo:[0,1] neg_hi:[0,1]
	v_pk_add_f32 v[86:87], v[86:87], v[162:163] op_sel_hi:[1,0] neg_lo:[0,1] neg_hi:[0,1]
	v_pk_add_f32 v[70:71], v[70:71], v[162:163] op_sel_hi:[1,0] neg_lo:[0,1] neg_hi:[0,1]
	v_pk_add_f32 v[88:89], v[88:89], v[162:163] op_sel_hi:[1,0] neg_lo:[0,1] neg_hi:[0,1]
	v_pk_add_f32 v[72:73], v[72:73], v[162:163] op_sel_hi:[1,0] neg_lo:[0,1] neg_hi:[0,1]
	v_pk_add_f32 v[90:91], v[90:91], v[162:163] op_sel_hi:[1,0] neg_lo:[0,1] neg_hi:[0,1]
	v_pk_add_f32 v[74:75], v[74:75], v[162:163] op_sel_hi:[1,0] neg_lo:[0,1] neg_hi:[0,1]
	v_pk_add_f32 v[92:93], v[92:93], v[162:163] op_sel_hi:[1,0] neg_lo:[0,1] neg_hi:[0,1]
	v_pk_add_f32 v[76:77], v[76:77], v[162:163] op_sel_hi:[1,0] neg_lo:[0,1] neg_hi:[0,1]
	v_pk_add_f32 v[94:95], v[94:95], v[162:163] op_sel_hi:[1,0] neg_lo:[0,1] neg_hi:[0,1]
	v_pk_add_f32 v[78:79], v[78:79], v[162:163] op_sel_hi:[1,0] neg_lo:[0,1] neg_hi:[0,1]
	v_pk_mul_f32 v[62:63], v[62:63], v[164:165] op_sel_hi:[1,0]
	v_pk_mul_f32 v[60:61], v[60:61], v[164:165] op_sel_hi:[1,0]
	v_pk_mul_f32 v[58:59], v[58:59], v[164:165] op_sel_hi:[1,0]
	v_pk_mul_f32 v[56:57], v[56:57], v[164:165] op_sel_hi:[1,0]
	v_pk_mul_f32 v[54:55], v[54:55], v[164:165] op_sel_hi:[1,0]
	v_pk_mul_f32 v[52:53], v[52:53], v[164:165] op_sel_hi:[1,0]
	v_pk_mul_f32 v[50:51], v[50:51], v[164:165] op_sel_hi:[1,0]
	v_pk_mul_f32 v[48:49], v[48:49], v[164:165] op_sel_hi:[1,0]
	v_pk_mul_f32 v[14:15], v[14:15], v[164:165] op_sel_hi:[1,0]
	v_pk_mul_f32 v[12:13], v[12:13], v[164:165] op_sel_hi:[1,0]
	v_pk_mul_f32 v[10:11], v[10:11], v[164:165] op_sel_hi:[1,0]
	v_pk_mul_f32 v[8:9], v[8:9], v[164:165] op_sel_hi:[1,0]
	v_pk_mul_f32 v[6:7], v[6:7], v[164:165] op_sel_hi:[1,0]
	v_pk_mul_f32 v[4:5], v[4:5], v[164:165] op_sel_hi:[1,0]
	v_pk_mul_f32 v[2:3], v[2:3], v[164:165] op_sel_hi:[1,0]
	v_pk_mul_f32 v[0:1], v[0:1], v[164:165] op_sel_hi:[1,0]
	v_pk_mul_f32 v[30:31], v[30:31], v[164:165] op_sel_hi:[1,0]
	v_pk_mul_f32 v[28:29], v[28:29], v[164:165] op_sel_hi:[1,0]
	v_pk_mul_f32 v[26:27], v[26:27], v[164:165] op_sel_hi:[1,0]
	v_pk_mul_f32 v[24:25], v[24:25], v[164:165] op_sel_hi:[1,0]
	v_pk_mul_f32 v[22:23], v[22:23], v[164:165] op_sel_hi:[1,0]
	v_pk_mul_f32 v[20:21], v[20:21], v[164:165] op_sel_hi:[1,0]
	v_pk_mul_f32 v[18:19], v[18:19], v[164:165] op_sel_hi:[1,0]
	v_pk_mul_f32 v[16:17], v[16:17], v[164:165] op_sel_hi:[1,0]
	v_sub_f32_e32 v47, v47, v162
	v_sub_f32_e32 v46, v46, v162
	v_sub_f32_e32 v45, v45, v162
	v_sub_f32_e32 v44, v44, v162
	v_sub_f32_e32 v43, v43, v162
	v_sub_f32_e32 v42, v42, v162
	v_sub_f32_e32 v41, v41, v162
	v_sub_f32_e32 v40, v40, v162
	v_sub_f32_e32 v39, v39, v162
	v_sub_f32_e32 v38, v38, v162
	v_sub_f32_e32 v37, v37, v162
	v_sub_f32_e32 v36, v36, v162
	v_sub_f32_e32 v35, v35, v162
	v_sub_f32_e32 v34, v34, v162
	v_sub_f32_e32 v33, v33, v162
	v_sub_f32_e32 v32, v32, v162
	s_branch .LBB0_109

; #define LAS __attribute__((address_space(3)))
; template <int KIND> ...
;     ...
;             if (t + 1 < nt) ATT_LOAD(t + 1);
;             bool active = true;
;             if (KIND == 0 && t < n1) { const int kr = kr_lo + t; active = (kr >= rs_w) && (kr < rs_w + 8); }
;             if (__builtin_amdgcn_readfirstlane((int)active)) {
;                 const int buf = t & 1;
;                 bf16x8 kf[8];
; #pragma unroll
;                 for (int t4 = 0; t4 < 4; ++t4) { kf[2 * t4] = *(const LAS bf16x8*)(lds + buf * KBUF + koff + 32 * t4); kf[2 * t4 + 1] = *(const LAS bf16x8*)(lds + buf * KBUF + koff + 32 * KSTR + 32 * t4); }
;                 __builtin_amdgcn_sched_barrier(0);
;                 f32x16 s0, s1;
; #pragma unroll
;                 for (int t4 = 0; t4 < 4; ++t4) {
;                     s0 = __builtin_amdgcn_mfma_f32_32x32x16_bf16(kf[2 * t4], qf[t4], t4 == 0 ? mneg : s0, 0, 0, 0);
;                     s1 = __builtin_amdgcn_mfma_f32_32x32x16_bf16(kf[2 * t4 + 1], qf[t4], t4 == 0 ? mneg : s1, 0, 0, 0);
;                 }
;                 float ab0[16], ab1[16];
;                 const bool na_lat = (KIND == 0) && (t < n1);
;                 if (na_lat) {
;                     const int bo = boff0 + (kr_lo + t - qr + 7) * 124;
; #pragma unroll
;                     for (int j = 0; j < 16; ++j) {
;                         const int C0 = 8 * (j >> 2) + (j & 3), C1 = 32 + C0;
;                         const float b0 = *(const LAS float*)(lds + bo + 4 * C0), b1 = *(const LAS float*)(lds + bo + 4 * C1);
;                         ab0[j] = ((unsigned)(wb + C0) < 16u) ? b0 : -1e30f;
;                         ab1[j] = ((unsigned)(wb + C1) < 16u) ? b1 : -1e30f;
;                     }
; #pragma unroll
;                     for (int i = 0; i < 8; ++i) { __builtin_amdgcn_sched_group_barrier(0x008, 1, 0); __builtin_amdgcn_sched_group_barrier(0x100, 4, 0); __builtin_amdgcn_sched_group_barrier(0x002, 12, 0); }
;                 }
;                 __builtin_amdgcn_sched_barrier(0);
;                 s16x4 vfa[2][NDT][2], vfb[2][NDT][2];
; #pragma unroll
;                 for (int s = 0; s < 2; ++s)
; #pragma unroll
;                     for (int dt = 0; dt < NDT; ++dt) {
;                         vfa[s][dt][0] = __builtin_amdgcn_ds_read_tr16_b64_v4i16((LAS s16x4*)(lds + buf * VBUF + voff + (16 * s) * VSTR + 64 * dt));
.LBB0_114:
	v_add_u32_e32 v64, s19, v155
	v_xor_b32_e32 v174, 32, v64
	v_xor_b32_e32 v175, 64, v64
	v_xor_b32_e32 v176, 0x60, v64
	ds_read_b128 v[80:83], v64
	ds_read_b128 v[84:87], v174
	ds_read_b128 v[88:91], v64 offset:4096
	ds_read_b128 v[92:95], v174 offset:4096
	ds_read_b128 v[120:123], v175
	ds_read_b128 v[124:127], v176
	ds_read_b128 v[128:131], v175 offset:4096
	ds_read_b128 v[132:135], v176 offset:4096
	s_waitcnt lgkmcnt(7)
	v_mfma_f32_32x32x16_bf16 v[64:79], v[80:83], v[116:119], v[32:47]
	s_waitcnt lgkmcnt(5)
	v_mfma_f32_32x32x16_bf16 v[32:47], v[88:91], v[116:119], v[32:47]
	v_mfma_f32_32x32x16_bf16 v[64:79], v[84:87], v[112:115], v[64:79]
	s_waitcnt lgkmcnt(4)
	v_mfma_f32_32x32x16_bf16 v[32:47], v[92:95], v[112:115], v[32:47]
	s_waitcnt lgkmcnt(3)
	v_mfma_f32_32x32x16_bf16 v[64:79], v[120:123], v[108:111], v[64:79]
	s_waitcnt lgkmcnt(1)
	v_mfma_f32_32x32x16_bf16 v[32:47], v[128:131], v[108:111], v[32:47]
	v_add_u32_e32 v108, s17, v156
	v_xor_b32_e32 v177, 64, v108
	ds_read_b64_tr_b16 v[92:93], v108 offset:16384
	ds_read_b64_tr_b16 v[94:95], v108 offset:17408
	ds_read_b64_tr_b16 v[90:91], v177 offset:17408
	ds_read_b64_tr_b16 v[88:89], v177 offset:16384
	ds_read_b64_tr_b16 v[84:85], v108 offset:18432
	ds_read_b64_tr_b16 v[86:87], v108 offset:19456
	ds_read_b64_tr_b16 v[82:83], v177 offset:19456
	ds_read_b64_tr_b16 v[80:81], v177 offset:18432
	v_mfma_f32_32x32x16_bf16 v[64:79], v[124:127], v[104:107], v[64:79]
	s_waitcnt lgkmcnt(8)
	v_mfma_f32_32x32x16_bf16 v[32:47], v[132:135], v[104:107], v[32:47]
	s_nop 9
	v_max_f32_e32 v104, v79, v79
	s_nop 0
	v_max_f32_e32 v105, v47, v47
	v_max_f32_e32 v104, v105, v104
	v_max3_f32 v105, v104, v64, v32
	v_max3_f32 v104, v104, v65, v33
	s_mov_b32 s5, 0x41000000
	v_max3_f32 v105, v105, v66, v34
	v_max3_f32 v104, v104, v67, v35
	s_nop 0
	v_max3_f32 v105, v105, v68, v36
	v_max3_f32 v104, v104, v69, v37
	s_nop 0
	v_max3_f32 v105, v105, v70, v38
	v_max3_f32 v104, v104, v71, v39
	s_nop 0
	v_max3_f32 v105, v105, v72, v40
	v_max3_f32 v104, v104, v73, v41
	s_nop 0
	v_max3_f32 v105, v105, v74, v42
	v_max3_f32 v104, v104, v75, v43
	s_nop 0
	v_max3_f32 v105, v105, v76, v44
	v_max3_f32 v104, v104, v77, v45
	s_nop 0
	v_max3_f32 v105, v105, v78, v46
	v_max3_f32 v104, v104, v79, v47
	s_nop 0
	v_max_f32_e32 v104, v104, v104
	v_max_f32_e32 v105, v105, v105
	v_max_f32_e32 v104, v105, v104
	v_cmp_lt_f32_e32 vcc, s5, v104
	s_cbranch_vccz .LBB0_116
	ds_bpermute_b32 v105, v157, v104
	s_waitcnt lgkmcnt(0)
	v_max3_f32 v104, v104, v105, 0
	v_exp_f32_e64 v106, -v104
	v_pk_add_f32 v[64:65], v[64:65], v[104:105] op_sel_hi:[1,0] neg_lo:[0,1] neg_hi:[0,1]
	v_pk_add_f32 v[32:33], v[32:33], v[104:105] op_sel_hi:[1,0] neg_lo:[0,1] neg_hi:[0,1]
	v_pk_add_f32 v[66:67], v[66:67], v[104:105] op_sel_hi:[1,0] neg_lo:[0,1] neg_hi:[0,1]
	v_pk_add_f32 v[34:35], v[34:35], v[104:105] op_sel_hi:[1,0] neg_lo:[0,1] neg_hi:[0,1]
	v_pk_add_f32 v[68:69], v[68:69], v[104:105] op_sel_hi:[1,0] neg_lo:[0,1] neg_hi:[0,1]
	v_pk_add_f32 v[36:37], v[36:37], v[104:105] op_sel_hi:[1,0] neg_lo:[0,1] neg_hi:[0,1]
	v_pk_add_f32 v[70:71], v[70:71], v[104:105] op_sel_hi:[1,0] neg_lo:[0,1] neg_hi:[0,1]
	v_pk_add_f32 v[38:39], v[38:39], v[104:105] op_sel_hi:[1,0] neg_lo:[0,1] neg_hi:[0,1]
	v_pk_add_f32 v[72:73], v[72:73], v[104:105] op_sel_hi:[1,0] neg_lo:[0,1] neg_hi:[0,1]
	v_pk_add_f32 v[40:41], v[40:41], v[104:105] op_sel_hi:[1,0] neg_lo:[0,1] neg_hi:[0,1]
	v_pk_add_f32 v[74:75], v[74:75], v[104:105] op_sel_hi:[1,0] neg_lo:[0,1] neg_hi:[0,1]
	v_pk_add_f32 v[42:43], v[42:43], v[104:105] op_sel_hi:[1,0] neg_lo:[0,1] neg_hi:[0,1]
	v_pk_add_f32 v[76:77], v[76:77], v[104:105] op_sel_hi:[1,0] neg_lo:[0,1] neg_hi:[0,1]
	v_pk_add_f32 v[44:45], v[44:45], v[104:105] op_sel_hi:[1,0] neg_lo:[0,1] neg_hi:[0,1]
	v_pk_add_f32 v[78:79], v[78:79], v[104:105] op_sel_hi:[1,0] neg_lo:[0,1] neg_hi:[0,1]
	v_pk_add_f32 v[46:47], v[46:47], v[104:105] op_sel_hi:[1,0] neg_lo:[0,1] neg_hi:[0,1]
	v_pk_mul_f32 v[62:63], v[62:63], v[106:107] op_sel_hi:[1,0]
	v_pk_mul_f32 v[60:61], v[60:61], v[106:107] op_sel_hi:[1,0]
	v_pk_mul_f32 v[58:59], v[58:59], v[106:107] op_sel_hi:[1,0]
	v_pk_mul_f32 v[56:57], v[56:57], v[106:107] op_sel_hi:[1,0]
	v_pk_mul_f32 v[54:55], v[54:55], v[106:107] op_sel_hi:[1,0]
	v_pk_mul_f32 v[52:53], v[52:53], v[106:107] op_sel_hi:[1,0]
	v_pk_mul_f32 v[50:51], v[50:51], v[106:107] op_sel_hi:[1,0]
	v_pk_mul_f32 v[48:49], v[48:49], v[106:107] op_sel_hi:[1,0]
	v_pk_mul_f32 v[14:15], v[14:15], v[106:107] op_sel_hi:[1,0]
	v_pk_mul_f32 v[12:13], v[12:13], v[106:107] op_sel_hi:[1,0]
	v_pk_mul_f32 v[10:11], v[10:11], v[106:107] op_sel_hi:[1,0]
	v_pk_mul_f32 v[8:9], v[8:9], v[106:107] op_sel_hi:[1,0]
	v_pk_mul_f32 v[6:7], v[6:7], v[106:107] op_sel_hi:[1,0]
	v_pk_mul_f32 v[4:5], v[4:5], v[106:107] op_sel_hi:[1,0]
	v_pk_mul_f32 v[2:3], v[2:3], v[106:107] op_sel_hi:[1,0]
	v_pk_mul_f32 v[0:1], v[0:1], v[106:107] op_sel_hi:[1,0]
	v_pk_mul_f32 v[30:31], v[30:31], v[106:107] op_sel_hi:[1,0]
	v_pk_mul_f32 v[28:29], v[28:29], v[106:107] op_sel_hi:[1,0]
	v_pk_mul_f32 v[26:27], v[26:27], v[106:107] op_sel_hi:[1,0]
	v_pk_mul_f32 v[24:25], v[24:25], v[106:107] op_sel_hi:[1,0]
	v_pk_mul_f32 v[22:23], v[22:23], v[106:107] op_sel_hi:[1,0]
	v_pk_mul_f32 v[20:21], v[20:21], v[106:107] op_sel_hi:[1,0]
	v_pk_mul_f32 v[18:19], v[18:19], v[106:107] op_sel_hi:[1,0]
	v_pk_mul_f32 v[16:17], v[16:17], v[106:107] op_sel_hi:[1,0]
; template <int KIND> ...
;     ...
; #pragma unroll
;                 for (int j = 0; j < 16; ++j) s0[j] = __builtin_amdgcn_exp2f(s0[j]);
;                 bf16x8 pf[4];
; #pragma unroll
;                 for (int s = 0; s < 2; ++s) { u32x4 w; w.x = pk2n(s0[8 * s + 0], s0[8 * s + 1]); w.y = pk2n(s0[8 * s + 2], s0[8 * s + 3]); w.z = pk2n(s0[8 * s + 4], s0[8 * s + 5]); w.w = pk2n(s0[8 * s + 6], s0[8 * s + 7]);
;                     pf[s] = __builtin_bit_cast(bf16x8, w); }
;                 __builtin_amdgcn_sched_barrier(0);
; #pragma unroll
;                 for (int s = 0; s < 2; ++s)
; #pragma unroll
;                     for (int dt = 0; dt < NDT; ++dt) {
;                         vfb[s][dt][0] = __builtin_amdgcn_ds_read_tr16_b64_v4i16((LAS s16x4*)(lds + buf * VBUF + voff + (16 * (s + 2)) * VSTR + 64 * dt));
;                         vfb[s][dt][1] = __builtin_amdgcn_ds_read_tr16_b64_v4i16((LAS s16x4*)(lds + buf * VBUF + voff + (16 * (s + 2) + 8) * VSTR + 64 * dt)); }
;                 {
;                     constexpr int NM = 2 * (1 + NDT);
;                     int mi = 0;
; #pragma unroll
;                     for (int s = 0; s < 2; ++s) {
;                         lacc = __builtin_amdgcn_mfma_f32_32x32x16_bf16(ones, pf[s], lacc, 0, 0, 0);
; #pragma unroll
;                         for (int j = (mi * 16) / NM; j < ((mi + 1) * 16) / NM; ++j) s1[j] = __builtin_amdgcn_exp2f(s1[j]);
;                         ++mi;
; #pragma unroll
;                         for (int dt = 0; dt < NDT; ++dt) {
;                             const s16x4 va = vfa[s][dt][0], vb = vfa[s][dt][1];
;                             const bf16x8 vf = {va[0], va[1], va[2], va[3], vb[0], vb[1], vb[2], vb[3]};
;                             o[dt] = __builtin_amdgcn_mfma_f32_32x32x16_bf16(vf, pf[s], o[dt], 0, 0, 0);
; #pragma unroll
;                             for (int j = (mi * 16) / NM; j < ((mi + 1) * 16) / NM; ++j) s1[j] = __builtin_amdgcn_exp2f(s1[j]);
;                             ++mi;
;                         }
;                     }
; #pragma unroll
;                     for (int q = 0; q < 2; ++q) { u32x4 w; w.x = pk2n(s1[8 * q + 0], s1[8 * q + 1]); w.y = pk2n(s1[8 * q + 2], s1[8 * q + 3]); w.z = pk2n(s1[8 * q + 4], s1[8 * q + 5]); w.w = pk2n(s1[8 * q + 6], s1[8 * q + 7]);
;                         pf[q + 2] = __builtin_bit_cast(bf16x8, w); }
; #pragma unroll
.LBB0_116:
	v_exp_f32_e32 v64, v64
	v_exp_f32_e32 v65, v65
	v_exp_f32_e32 v66, v66
	v_exp_f32_e32 v67, v67
	v_exp_f32_e32 v68, v68
	v_exp_f32_e32 v69, v69
	v_exp_f32_e32 v70, v70
	v_exp_f32_e32 v71, v71
	v_exp_f32_e32 v72, v72
	v_exp_f32_e32 v73, v73
	v_exp_f32_e32 v74, v74
	v_exp_f32_e32 v75, v75
	v_exp_f32_e32 v76, v76
	v_exp_f32_e32 v77, v77
	v_exp_f32_e32 v78, v78
	v_exp_f32_e32 v79, v79
	v_cvt_pk_bf16_f32 v64, v64, v65
	v_cvt_pk_bf16_f32 v65, v66, v67
	v_cvt_pk_bf16_f32 v66, v68, v69
	v_cvt_pk_bf16_f32 v67, v70, v71
	v_cvt_pk_bf16_f32 v68, v72, v73
	v_cvt_pk_bf16_f32 v69, v74, v75
	v_cvt_pk_bf16_f32 v70, v76, v77
	v_cvt_pk_bf16_f32 v71, v78, v79
	s_waitcnt lgkmcnt(6)
	v_mfma_f32_32x32x16_bf16 v[16:31], v[92:95], v[64:67], v[16:31]
	v_mov_b64_e32 v[72:73], s[84:85]
	v_mov_b64_e32 v[74:75], s[86:87]
	v_exp_f32_e32 v76, v32
	v_exp_f32_e32 v77, v33
	ds_read_b64_tr_b16 v[32:33], v108 offset:20480
	v_mfma_f32_32x32x16_bf16 v[48:63], v[72:75], v[64:67], v[48:63]
	v_exp_f32_e32 v78, v34
	v_exp_f32_e32 v79, v35
	v_exp_f32_e32 v92, v36
	v_exp_f32_e32 v93, v37
	ds_read_b64_tr_b16 v[34:35], v108 offset:21504
	ds_read_b64_tr_b16 v[36:37], v177 offset:20480
	s_waitcnt lgkmcnt(7)
	v_mfma_f32_32x32x16_bf16 v[0:15], v[88:91], v[64:67], v[0:15]
	v_exp_f32_e32 v94, v38
	v_exp_f32_e32 v95, v39
	v_exp_f32_e32 v88, v40
	v_exp_f32_e32 v89, v41
	ds_read_b64_tr_b16 v[38:39], v177 offset:21504
	ds_read_b64_tr_b16 v[40:41], v108 offset:22528
	v_mfma_f32_32x32x16_bf16 v[48:63], v[72:75], v[68:71], v[48:63]
	v_exp_f32_e32 v90, v42
	v_exp_f32_e32 v91, v43
	v_exp_f32_e32 v104, v44
	v_exp_f32_e32 v105, v45
	ds_read_b64_tr_b16 v[42:43], v108 offset:23552
	ds_read_b64_tr_b16 v[44:45], v177 offset:22528
	s_waitcnt lgkmcnt(9)
	v_mfma_f32_32x32x16_bf16 v[16:31], v[84:87], v[68:71], v[16:31]
	v_exp_f32_e32 v106, v46
	v_exp_f32_e32 v107, v47
	v_cvt_pk_bf16_f32 v64, v76, v77
	v_cvt_pk_bf16_f32 v65, v78, v79
	ds_read_b64_tr_b16 v[46:47], v177 offset:23552
	s_waitcnt lgkmcnt(8)
	v_mfma_f32_32x32x16_bf16 v[0:15], v[80:83], v[68:71], v[0:15]
	v_cvt_pk_bf16_f32 v66, v92, v93
	v_cvt_pk_bf16_f32 v67, v94, v95
	v_cvt_pk_bf16_f32 v68, v88, v89
	v_cvt_pk_bf16_f32 v69, v90, v91
	v_cvt_pk_bf16_f32 v70, v104, v105
	v_cvt_pk_bf16_f32 v71, v106, v107
	s_waitcnt lgkmcnt(6)
	v_mfma_f32_32x32x16_bf16 v[16:31], v[32:35], v[64:67], v[16:31]
	s_waitcnt lgkmcnt(4)
	v_mfma_f32_32x32x16_bf16 v[0:15], v[36:39], v[64:67], v[0:15]
	v_mfma_f32_32x32x16_bf16 v[48:63], v[72:75], v[64:67], v[48:63]
	s_waitcnt lgkmcnt(2)
	v_mfma_f32_32x32x16_bf16 v[16:31], v[40:43], v[68:71], v[16:31]
	s_waitcnt lgkmcnt(0)
	v_mfma_f32_32x32x16_bf16 v[0:15], v[44:47], v[68:71], v[0:15]
	v_mfma_f32_32x32x16_bf16 v[48:63], v[72:75], v[68:71], v[48:63]
	s_andn2_b64 vcc, exec, s[10:11]
	s_cbranch_vccnz .LBB0_99
	s_waitcnt vmcnt(1)
	ds_write_b128 v153, v[96:99]
	s_waitcnt vmcnt(0)
	ds_write_b128 v154, v[100:103] offset:18432
	s_branch .LBB0_99
